# v6 + Z epilogue stores: plain for the conv columns b_a/c_a/x_a (pn<12, consumed first in P2), nt for the rest
# speedup vs baseline: 1.0037x; 1.0037x over previous
; __device__ __forceinline__ unsigned pk2(float lo, float hi) { f32x2_t v = {lo, hi}; bf16x2_t b = __builtin_convertvector(v, bf16x2_t); return __builtin_bit_cast(unsigned, b); }
;     __device__ __forceinline__ void operator()(const f32x4 (&acc)[2][2][4][2], const pg8::Unit& u, int wr, int wc, int fr, int fq) const {
;         const int row0 = u.pm * 256 + wr * 64 + fr, col0 = u.pn * 256 + wc * 32 + 8 * fq;
; #pragma unroll
;         for (int ai = 0; ai < 2; ++ai)
; #pragma unroll
;             for (int m = 0; m < 4; ++m) { bf16* rowp = O + (size_t)(row0 + ai * 128 + m * 16) * ldc + col0;
; #pragma unroll
;                 for (int bj = 0; bj < 2; ++bj) { const f32x4 v0 = acc[ai][bj][m][0], v1 = acc[ai][bj][m][1];
;                     u32x4 w; w.x = pk2(v0[0], v0[1]); w.y = pk2(v0[2], v0[3]); w.z = pk2(v1[0], v1[1]); w.w = pk2(v1[2], v1[3]);
;                     *(u32x4*)(rowp + bj * 128) = w; } }
.LBB0_181:
	s_cmp_lt_u32 s46, 12
	s_cbranch_scc1 .Lepi_plain
	v_lshl_add_u32 v152, s18, 8, v145
	v_lshl_or_b32 v154, s46, 8, v147
	v_ashrrev_i32_e32 v153, 31, v152
	v_ashrrev_i32_e32 v155, 31, v154
	v_lshlrev_b64 v[156:157], 14, v[152:153]
	v_lshl_add_u64 v[156:157], s[72:73], 0, v[156:157]
	v_lshlrev_b64 v[154:155], 1, v[154:155]
	v_lshl_add_u64 v[156:157], v[156:157], 0, v[154:155]
	s_mov_b32 s18, 0x200000
	s_mov_b64 s[28:29], 0x200000
	v_cvt_pk_bf16_f32 v60, v60, v61
	v_cvt_pk_bf16_f32 v61, v62, v63
	v_cvt_pk_bf16_f32 v62, v56, v57
	v_add_co_u32_e32 v56, vcc, s18, v156
	v_cvt_pk_bf16_f32 v68, v68, v69
	v_cvt_pk_bf16_f32 v69, v70, v71
	v_cvt_pk_bf16_f32 v70, v64, v65
	v_lshl_add_u64 v[64:65], v[156:157], 0, s[28:29]
	v_addc_co_u32_e32 v57, vcc, 0, v157, vcc
	v_cvt_pk_bf16_f32 v44, v44, v45
	v_cvt_pk_bf16_f32 v45, v46, v47
	v_cvt_pk_bf16_f32 v46, v40, v41
	v_cvt_pk_bf16_f32 v47, v42, v43
	s_mov_b32 s18, 0x240000
	v_cvt_pk_bf16_f32 v108, v108, v109
	v_cvt_pk_bf16_f32 v109, v110, v111
	v_cvt_pk_bf16_f32 v110, v104, v105
	v_or_b32_e32 v104, 16, v152
	global_store_dwordx4 v[64:65], v[44:47], off offset:256 nt
	s_mov_b64 s[28:29], 0x240000
	v_ashrrev_i32_e32 v105, 31, v104
	v_add_co_u32_e32 v46, vcc, s18, v156
	v_cvt_pk_bf16_f32 v92, v92, v93
	v_cvt_pk_bf16_f32 v93, v94, v95
	v_cvt_pk_bf16_f32 v94, v88, v89
	v_or_b32_e32 v88, 32, v152
	v_lshl_add_u64 v[44:45], v[156:157], 0, s[28:29]
	v_addc_co_u32_e32 v47, vcc, 0, v157, vcc
	v_cvt_pk_bf16_f32 v28, v28, v29
	v_cvt_pk_bf16_f32 v29, v30, v31
	v_cvt_pk_bf16_f32 v30, v24, v25
	v_cvt_pk_bf16_f32 v31, v26, v27
	s_mov_b32 s18, 0x280000
	v_lshlrev_b64 v[104:105], 14, v[104:105]
	v_ashrrev_i32_e32 v89, 31, v88
	v_cvt_pk_bf16_f32 v76, v76, v77
	v_cvt_pk_bf16_f32 v77, v78, v79
	v_cvt_pk_bf16_f32 v78, v72, v73
	v_or_b32_e32 v72, 48, v152
	global_store_dwordx4 v[44:45], v[28:31], off offset:256 nt
	s_mov_b64 s[28:29], 0x280000
	v_cvt_pk_bf16_f32 v111, v106, v107
	v_add_co_u32_e32 v30, vcc, s18, v156
	v_lshl_add_u64 v[104:105], s[72:73], 0, v[104:105]
	v_lshlrev_b64 v[88:89], 14, v[88:89]
	v_ashrrev_i32_e32 v73, 31, v72
	v_lshl_add_u64 v[28:29], v[156:157], 0, s[28:29]
	v_addc_co_u32_e32 v31, vcc, 0, v157, vcc
	v_cvt_pk_bf16_f32 v12, v12, v13
	v_cvt_pk_bf16_f32 v13, v14, v15
	v_cvt_pk_bf16_f32 v14, v8, v9
	v_cvt_pk_bf16_f32 v15, v10, v11
	s_mov_b32 s18, 0x2c0000
	global_store_dwordx4 v[156:157], v[108:111], off offset:256 nt
	v_cvt_pk_bf16_f32 v95, v90, v91
	v_lshl_add_u64 v[88:89], s[72:73], 0, v[88:89]
	v_lshl_add_u64 v[108:109], v[104:105], 0, v[154:155]
	v_lshlrev_b64 v[72:73], 14, v[72:73]
	global_store_dwordx4 v[28:29], v[12:15], off offset:256 nt
	global_store_dwordx4 v[108:109], v[92:95], off offset:256 nt
	v_cvt_pk_bf16_f32 v79, v74, v75
	v_add_co_u32_e32 v14, vcc, s18, v156
	v_lshl_add_u64 v[92:93], v[88:89], 0, v[154:155]
	v_lshl_add_u64 v[72:73], s[72:73], 0, v[72:73]
	s_mov_b64 s[28:29], 0x2c0000
	v_addc_co_u32_e32 v15, vcc, 0, v157, vcc
	v_cvt_pk_bf16_f32 v124, v124, v125
	v_cvt_pk_bf16_f32 v125, v126, v127
	v_cvt_pk_bf16_f32 v126, v120, v121
	v_cvt_pk_bf16_f32 v127, v122, v123
	v_cvt_pk_bf16_f32 v104, v116, v117
	v_cvt_pk_bf16_f32 v105, v118, v119
	v_cvt_pk_bf16_f32 v106, v112, v113
	v_cvt_pk_bf16_f32 v107, v114, v115
	v_cvt_pk_bf16_f32 v88, v100, v101
	v_cvt_pk_bf16_f32 v89, v102, v103
	v_cvt_pk_bf16_f32 v90, v96, v97
	v_cvt_pk_bf16_f32 v91, v98, v99
	global_store_dwordx4 v[92:93], v[76:79], off offset:256 nt
	v_cvt_pk_bf16_f32 v74, v80, v81
	v_cvt_pk_bf16_f32 v75, v82, v83
	v_lshl_add_u64 v[76:77], v[72:73], 0, v[154:155]
	v_cvt_pk_bf16_f32 v72, v84, v85
	v_cvt_pk_bf16_f32 v73, v86, v87
	v_cvt_pk_bf16_f32 v71, v66, v67
	v_cvt_pk_bf16_f32 v63, v58, v59
	v_cvt_pk_bf16_f32 v40, v52, v53
	v_cvt_pk_bf16_f32 v41, v54, v55
	v_cvt_pk_bf16_f32 v42, v48, v49
	v_cvt_pk_bf16_f32 v43, v50, v51
	v_cvt_pk_bf16_f32 v24, v36, v37
	v_cvt_pk_bf16_f32 v25, v38, v39
	v_cvt_pk_bf16_f32 v26, v32, v33
	v_cvt_pk_bf16_f32 v27, v34, v35
	v_lshl_add_u64 v[12:13], v[156:157], 0, s[28:29]
	v_cvt_pk_bf16_f32 v8, v20, v21
	v_cvt_pk_bf16_f32 v9, v22, v23
	v_cvt_pk_bf16_f32 v10, v16, v17
	v_cvt_pk_bf16_f32 v11, v18, v19
	v_cvt_pk_bf16_f32 v4, v4, v5
	v_cvt_pk_bf16_f32 v5, v6, v7
	v_cvt_pk_bf16_f32 v6, v0, v1
	v_cvt_pk_bf16_f32 v7, v2, v3
	s_andn2_b64 vcc, exec, s[0:1]
	s_mov_b64 s[0:1], -1
	global_store_dwordx4 v[156:157], v[124:127], off nt
	global_store_dwordx4 v[108:109], v[104:107], off nt
	global_store_dwordx4 v[92:93], v[88:91], off nt
	global_store_dwordx4 v[76:77], v[72:75], off nt
	global_store_dwordx4 v[76:77], v[68:71], off offset:256 nt
	global_store_dwordx4 v[56:57], v[60:63], off nt
	global_store_dwordx4 v[46:47], v[40:43], off nt
	global_store_dwordx4 v[30:31], v[24:27], off nt
	global_store_dwordx4 v[14:15], v[8:11], off nt
	global_store_dwordx4 v[12:13], v[4:7], off offset:256 nt
; #define PG8_BAR __builtin_amdgcn_s_barrier()
; __device__ __forceinline__ unsigned pk2(float lo, float hi) { f32x2_t v = {lo, hi}; bf16x2_t b = __builtin_convertvector(v, bf16x2_t); return __builtin_bit_cast(unsigned, b); }
; template <class Epi, class Sched, bool ALIGN_EPI = false, bool SP2 = false>
; __device__ __forceinline__ void gemm_phase(PG8_LAS unsigned char* lds, const Gemm g, const Sched& S, const Epi& E) {
;     ...
;         if (!has_next) break;
; #pragma unroll
;         for (int a = 0; a < 2; ++a)
; #pragma unroll
;             for (int b = 0; b < 2; ++b)
; #pragma unroll
;                 for (int m = 0; m < 4; ++m)
; #pragma unroll
;                     for (int n = 0; n < 2; ++n) acc[a][b][m][n] = (f32x4){0.f, 0.f, 0.f, 0.f};
;         cur = nxt; cA = nA; cB = nB; ++ui;
;         if constexpr (ALIGN_EPI) { if (wr == 1) PG8_BAR; }
;     __device__ __forceinline__ void operator()(const f32x4 (&acc)[2][2][4][2], const pg8::Unit& u, int wr, int wc, int fr, int fq) const {
;         const int row0 = u.pm * 256 + wr * 64 + fr, col0 = u.pn * 256 + wc * 32 + 8 * fq;
; #pragma unroll
;         for (int ai = 0; ai < 2; ++ai)
; #pragma unroll
;             for (int m = 0; m < 4; ++m) { bf16* rowp = O + (size_t)(row0 + ai * 128 + m * 16) * ldc + col0;
; #pragma unroll
;                 for (int bj = 0; bj < 2; ++bj) { const f32x4 v0 = acc[ai][bj][m][0], v1 = acc[ai][bj][m][1];
;                     u32x4 w; w.x = pk2(v0[0], v0[1]); w.y = pk2(v0[2], v0[3]); w.z = pk2(v1[0], v1[1]); w.w = pk2(v1[2], v1[3]);
;                     *(u32x4*)(rowp + bj * 128) = w; } }
.Lepi_join:
	s_cbranch_vccnz .LBB0_170
	s_andn2_b64 vcc, exec, s[4:5]
	s_cbranch_vccnz .LBB0_169
	s_barrier
	s_branch .LBB0_169
.Lepi_plain:
	v_lshl_add_u32 v152, s18, 8, v145
	v_lshl_or_b32 v154, s46, 8, v147
	v_ashrrev_i32_e32 v153, 31, v152
	v_ashrrev_i32_e32 v155, 31, v154
	v_lshlrev_b64 v[156:157], 14, v[152:153]
	v_lshl_add_u64 v[156:157], s[72:73], 0, v[156:157]
	v_lshlrev_b64 v[154:155], 1, v[154:155]
	v_lshl_add_u64 v[156:157], v[156:157], 0, v[154:155]
	s_mov_b32 s18, 0x200000
	s_mov_b64 s[28:29], 0x200000
	v_cvt_pk_bf16_f32 v60, v60, v61
	v_cvt_pk_bf16_f32 v61, v62, v63
	v_cvt_pk_bf16_f32 v62, v56, v57
	v_add_co_u32_e32 v56, vcc, s18, v156
	v_cvt_pk_bf16_f32 v68, v68, v69
	v_cvt_pk_bf16_f32 v69, v70, v71
	v_cvt_pk_bf16_f32 v70, v64, v65
	v_lshl_add_u64 v[64:65], v[156:157], 0, s[28:29]
	v_addc_co_u32_e32 v57, vcc, 0, v157, vcc
	v_cvt_pk_bf16_f32 v44, v44, v45
	v_cvt_pk_bf16_f32 v45, v46, v47
	v_cvt_pk_bf16_f32 v46, v40, v41
	v_cvt_pk_bf16_f32 v47, v42, v43
	s_mov_b32 s18, 0x240000
	v_cvt_pk_bf16_f32 v108, v108, v109
	v_cvt_pk_bf16_f32 v109, v110, v111
	v_cvt_pk_bf16_f32 v110, v104, v105
	v_or_b32_e32 v104, 16, v152
	global_store_dwordx4 v[64:65], v[44:47], off offset:256
	s_mov_b64 s[28:29], 0x240000
	v_ashrrev_i32_e32 v105, 31, v104
	v_add_co_u32_e32 v46, vcc, s18, v156
	v_cvt_pk_bf16_f32 v92, v92, v93
	v_cvt_pk_bf16_f32 v93, v94, v95
	v_cvt_pk_bf16_f32 v94, v88, v89
	v_or_b32_e32 v88, 32, v152
	v_lshl_add_u64 v[44:45], v[156:157], 0, s[28:29]
	v_addc_co_u32_e32 v47, vcc, 0, v157, vcc
	v_cvt_pk_bf16_f32 v28, v28, v29
	v_cvt_pk_bf16_f32 v29, v30, v31
	v_cvt_pk_bf16_f32 v30, v24, v25
	v_cvt_pk_bf16_f32 v31, v26, v27
	s_mov_b32 s18, 0x280000
	v_lshlrev_b64 v[104:105], 14, v[104:105]
	v_ashrrev_i32_e32 v89, 31, v88
	v_cvt_pk_bf16_f32 v76, v76, v77
	v_cvt_pk_bf16_f32 v77, v78, v79
	v_cvt_pk_bf16_f32 v78, v72, v73
	v_or_b32_e32 v72, 48, v152
	global_store_dwordx4 v[44:45], v[28:31], off offset:256
	s_mov_b64 s[28:29], 0x280000
	v_cvt_pk_bf16_f32 v111, v106, v107
	v_add_co_u32_e32 v30, vcc, s18, v156
	v_lshl_add_u64 v[104:105], s[72:73], 0, v[104:105]
	v_lshlrev_b64 v[88:89], 14, v[88:89]
	v_ashrrev_i32_e32 v73, 31, v72
	v_lshl_add_u64 v[28:29], v[156:157], 0, s[28:29]
	v_addc_co_u32_e32 v31, vcc, 0, v157, vcc
	v_cvt_pk_bf16_f32 v12, v12, v13
	v_cvt_pk_bf16_f32 v13, v14, v15
	v_cvt_pk_bf16_f32 v14, v8, v9
	v_cvt_pk_bf16_f32 v15, v10, v11
	s_mov_b32 s18, 0x2c0000
	global_store_dwordx4 v[156:157], v[108:111], off offset:256
	v_cvt_pk_bf16_f32 v95, v90, v91
	v_lshl_add_u64 v[88:89], s[72:73], 0, v[88:89]
	v_lshl_add_u64 v[108:109], v[104:105], 0, v[154:155]
	v_lshlrev_b64 v[72:73], 14, v[72:73]
	global_store_dwordx4 v[28:29], v[12:15], off offset:256
	global_store_dwordx4 v[108:109], v[92:95], off offset:256
	v_cvt_pk_bf16_f32 v79, v74, v75
	v_add_co_u32_e32 v14, vcc, s18, v156
	v_lshl_add_u64 v[92:93], v[88:89], 0, v[154:155]
	v_lshl_add_u64 v[72:73], s[72:73], 0, v[72:73]
	s_mov_b64 s[28:29], 0x2c0000
	v_addc_co_u32_e32 v15, vcc, 0, v157, vcc
	v_cvt_pk_bf16_f32 v124, v124, v125
	v_cvt_pk_bf16_f32 v125, v126, v127
	v_cvt_pk_bf16_f32 v126, v120, v121
	v_cvt_pk_bf16_f32 v127, v122, v123
	v_cvt_pk_bf16_f32 v104, v116, v117
	v_cvt_pk_bf16_f32 v105, v118, v119
	v_cvt_pk_bf16_f32 v106, v112, v113
	v_cvt_pk_bf16_f32 v107, v114, v115
	v_cvt_pk_bf16_f32 v88, v100, v101
	v_cvt_pk_bf16_f32 v89, v102, v103
	v_cvt_pk_bf16_f32 v90, v96, v97
	v_cvt_pk_bf16_f32 v91, v98, v99
	global_store_dwordx4 v[92:93], v[76:79], off offset:256
	v_cvt_pk_bf16_f32 v74, v80, v81
	v_cvt_pk_bf16_f32 v75, v82, v83
	v_lshl_add_u64 v[76:77], v[72:73], 0, v[154:155]
	v_cvt_pk_bf16_f32 v72, v84, v85
	v_cvt_pk_bf16_f32 v73, v86, v87
	v_cvt_pk_bf16_f32 v71, v66, v67
	v_cvt_pk_bf16_f32 v63, v58, v59
	v_cvt_pk_bf16_f32 v40, v52, v53
	v_cvt_pk_bf16_f32 v41, v54, v55
	v_cvt_pk_bf16_f32 v42, v48, v49
	v_cvt_pk_bf16_f32 v43, v50, v51
	v_cvt_pk_bf16_f32 v24, v36, v37
	v_cvt_pk_bf16_f32 v25, v38, v39
	v_cvt_pk_bf16_f32 v26, v32, v33
	v_cvt_pk_bf16_f32 v27, v34, v35
	v_lshl_add_u64 v[12:13], v[156:157], 0, s[28:29]
	v_cvt_pk_bf16_f32 v8, v20, v21
	v_cvt_pk_bf16_f32 v9, v22, v23
	v_cvt_pk_bf16_f32 v10, v16, v17
	v_cvt_pk_bf16_f32 v11, v18, v19
	v_cvt_pk_bf16_f32 v4, v4, v5
	v_cvt_pk_bf16_f32 v5, v6, v7
	v_cvt_pk_bf16_f32 v6, v0, v1
	v_cvt_pk_bf16_f32 v7, v2, v3
	s_andn2_b64 vcc, exec, s[0:1]
	s_mov_b64 s[0:1], -1
	global_store_dwordx4 v[156:157], v[124:127], off
	global_store_dwordx4 v[108:109], v[104:107], off
	global_store_dwordx4 v[92:93], v[88:91], off
	global_store_dwordx4 v[76:77], v[72:75], off
	global_store_dwordx4 v[76:77], v[68:71], off offset:256
	global_store_dwordx4 v[56:57], v[60:63], off
	global_store_dwordx4 v[46:47], v[40:43], off
	global_store_dwordx4 v[30:31], v[24:27], off
	global_store_dwordx4 v[14:15], v[8:11], off
	global_store_dwordx4 v[12:13], v[4:7], off offset:256
	s_branch .Lepi_join
